# indexer: wave-uniform round test shortened (scalar compare of the lane mask instead of the cndmask / cmp_ne ballot chain between the two barriers)
# baseline (speedup 1.0000x reference)
; __device__ void indexer_item(LAS unsigned char* lds, const bf16_t* Qi, const bf16_t* Ki, const float* Wi, unsigned* maskout, int qt) {
;     ...
;             const unsigned both = (lane < 16) ? cnt[lane] + cnt[cnoff + lane] : 0u;
;             if (tid < 16) cnt[(cnoff ^ 32) + tid] = 0u;
;             round = __ballot(both > 512u) != 0ull;
;             if (round) {
; #pragma unroll 1
;                 for (int qq = 0; qq < 2; ++qq) { const int qi = 2 * wid + qq; const unsigned cc = cnt[qi], cn = cnt[cnoff + qi];
;                     if (cc + cn > 512u || cc > 320u) {
;                         if (cn > 192u || cc <= 320u) select256<true>(lds, qi, wid, lane); else select256<false>(lds, qi, wid, lane); } }
.LBB0_640:
	s_or_b64 exec, exec, s[28:29]
	s_and_saveexec_b64 s[28:29], s[8:9]
	s_xor_b32 s31, s30, 32
	v_lshl_add_u32 v33, s31, 2, v83
	ds_write_b32 v33, v155
	s_or_b64 exec, exec, s[28:29]
	s_cmp_lg_u64 s[26:27], 0
	s_cselect_b64 s[66:67], -1, 0
	s_cbranch_scc0 .LBB0_726
	s_lshl_b32 s26, s30, 2
	s_add_i32 s91, s26, 0
	s_add_i32 s91, s91, 0x18900
	s_mov_b32 s26, 0
	s_mov_b64 s[68:69], -1
	s_branch .LBB0_646
